# scalar-base + 32-bit-offset LDS-DMA addressing also in the in_proj and down K-loops
# baseline (speedup 1.0000x reference)
.LBB0_811:
	s_add_u32 s42, s44, 0x100
	s_addc_u32 s43, s45, 0
	s_add_i32 s18, 0, 0x10000
	s_cmp_eq_u32 s15, 40
	s_cselect_b32 s25, s11, s43
	s_cselect_b32 s24, s10, s42
	s_cselect_b32 s23, s17, s14
	s_cselect_b32 s22, s16, s13
	s_add_i32 s62, 0, 0x14000
	v_add_u32_e32 v156, s18, v210
	v_add_u32_e32 v172, s62, v210
	ds_read_b128 v[144:147], v156
	ds_read_b128 v[148:151], v156 offset:1024
	ds_read_b128 v[152:155], v156 offset:2048
	ds_read_b128 v[156:159], v156 offset:3072
	ds_read_b128 v[160:163], v172
	ds_read_b128 v[164:167], v172 offset:1024
	ds_read_b128 v[168:171], v172 offset:2048
	ds_read_b128 v[172:175], v172 offset:3072
	s_add_i32 m0, s47, 0xc000
	ds_read_b128 v[176:179], v212
	ds_read_b128 v[180:183], v212 offset:1024
	ds_read_b128 v[184:187], v212 offset:2048
	ds_read_b128 v[214:217], v212 offset:3072
	ds_read_b128 v[218:221], v212 offset:4096
	ds_read_b128 v[222:225], v212 offset:5120
	ds_read_b128 v[226:229], v212 offset:6144
	ds_read_b128 v[230:233], v212 offset:7168
	global_load_lds_dwordx4 v140, s[44:45]
	s_add_i32 m0, s47, 0xe000
	s_nop 0
	global_load_lds_dwordx4 v142, s[44:45]
	s_waitcnt vmcnt(8)
	s_waitcnt lgkmcnt(0)
	s_barrier
	s_setprio 1
	s_waitcnt lgkmcnt(0)
	v_mfma_f32_16x16x32_bf16 v[128:131], v[144:147], v[176:179], v[128:131]
	v_mfma_f32_16x16x32_bf16 v[124:127], v[152:155], v[176:179], v[124:127]
	v_mfma_f32_16x16x32_bf16 v[112:115], v[144:147], v[184:187], v[112:115]
	v_mfma_f32_16x16x32_bf16 v[108:111], v[152:155], v[184:187], v[108:111]
	v_mfma_f32_16x16x32_bf16 v[96:99], v[144:147], v[218:221], v[96:99]
	v_mfma_f32_16x16x32_bf16 v[92:95], v[152:155], v[218:221], v[92:95]
	v_mfma_f32_16x16x32_bf16 v[80:83], v[144:147], v[226:229], v[80:83]
	v_mfma_f32_16x16x32_bf16 v[76:79], v[152:155], v[226:229], v[76:79]
	v_mfma_f32_16x16x32_bf16 v[128:131], v[148:151], v[180:183], v[128:131]
	v_mfma_f32_16x16x32_bf16 v[124:127], v[156:159], v[180:183], v[124:127]
	v_mfma_f32_16x16x32_bf16 v[112:115], v[148:151], v[214:217], v[112:115]
	v_mfma_f32_16x16x32_bf16 v[108:111], v[156:159], v[214:217], v[108:111]
	v_mfma_f32_16x16x32_bf16 v[96:99], v[148:151], v[222:225], v[96:99]
	v_mfma_f32_16x16x32_bf16 v[92:95], v[156:159], v[222:225], v[92:95]
	v_mfma_f32_16x16x32_bf16 v[80:83], v[148:151], v[230:233], v[80:83]
	v_mfma_f32_16x16x32_bf16 v[76:79], v[156:159], v[230:233], v[76:79]
	s_setprio 0
	s_setprio 1
	v_mfma_f32_16x16x32_bf16 v[120:123], v[160:163], v[176:179], v[120:123]
	v_mfma_f32_16x16x32_bf16 v[116:119], v[168:171], v[176:179], v[116:119]
	v_mfma_f32_16x16x32_bf16 v[104:107], v[160:163], v[184:187], v[104:107]
	v_mfma_f32_16x16x32_bf16 v[100:103], v[168:171], v[184:187], v[100:103]
	v_mfma_f32_16x16x32_bf16 v[88:91], v[160:163], v[218:221], v[88:91]
	v_mfma_f32_16x16x32_bf16 v[84:87], v[168:171], v[218:221], v[84:87]
	v_mfma_f32_16x16x32_bf16 v[72:75], v[160:163], v[226:229], v[72:75]
	v_mfma_f32_16x16x32_bf16 v[68:71], v[168:171], v[226:229], v[68:71]
	v_mfma_f32_16x16x32_bf16 v[120:123], v[164:167], v[180:183], v[120:123]
	v_mfma_f32_16x16x32_bf16 v[116:119], v[172:175], v[180:183], v[116:119]
	v_mfma_f32_16x16x32_bf16 v[104:107], v[164:167], v[214:217], v[104:107]
	v_mfma_f32_16x16x32_bf16 v[100:103], v[172:175], v[214:217], v[100:103]
	v_mfma_f32_16x16x32_bf16 v[88:91], v[164:167], v[222:225], v[88:91]
	v_mfma_f32_16x16x32_bf16 v[84:87], v[172:175], v[222:225], v[84:87]
	v_mfma_f32_16x16x32_bf16 v[72:75], v[164:167], v[230:233], v[72:75]
	v_mfma_f32_16x16x32_bf16 v[68:71], v[172:175], v[230:233], v[68:71]
	s_setprio 0
	s_barrier
	s_add_i32 s18, s18, s46
	s_mov_b32 m0, s18
	ds_read_b128 v[176:179], v212 offset:16384
	ds_read_b128 v[180:183], v212 offset:17408
	ds_read_b128 v[184:187], v212 offset:18432
	ds_read_b128 v[214:217], v212 offset:19456
	ds_read_b128 v[218:221], v212 offset:20480
	ds_read_b128 v[222:225], v212 offset:21504
	ds_read_b128 v[226:229], v212 offset:22528
	ds_read_b128 v[230:233], v212 offset:23552
	global_load_lds_dwordx4 v2, s[22:23]
	s_add_i32 m0, s18, 0x2000
	s_add_u32 s18, s22, 0xb0000
	s_addc_u32 s19, s23, 0
	s_add_i32 s44, s62, s46
	global_load_lds_dwordx4 v0, s[22:23]
	s_mov_b32 m0, s44
	s_nop 0
	global_load_lds_dwordx4 v2, s[18:19]
	s_add_i32 m0, s44, 0x2000
	s_nop 0
	global_load_lds_dwordx4 v0, s[18:19]
	s_mov_b32 m0, s47
	s_nop 0
	global_load_lds_dwordx4 v2, s[24:25]
	s_mov_b32 m0, s48
	s_nop 0
	global_load_lds_dwordx4 v0, s[24:25]
	s_waitcnt vmcnt(8)
	s_waitcnt lgkmcnt(0)
	s_barrier
	s_setprio 1
	s_waitcnt lgkmcnt(0)
	v_mfma_f32_16x16x32_bf16 v[64:67], v[144:147], v[176:179], v[64:67]
	v_mfma_f32_16x16x32_bf16 v[60:63], v[152:155], v[176:179], v[60:63]
	v_mfma_f32_16x16x32_bf16 v[48:51], v[144:147], v[184:187], v[48:51]
	v_mfma_f32_16x16x32_bf16 v[44:47], v[152:155], v[184:187], v[44:47]
	v_mfma_f32_16x16x32_bf16 v[32:35], v[144:147], v[218:221], v[32:35]
	v_mfma_f32_16x16x32_bf16 v[28:31], v[152:155], v[218:221], v[28:31]
	v_mfma_f32_16x16x32_bf16 v[16:19], v[144:147], v[226:229], v[16:19]
	v_mfma_f32_16x16x32_bf16 v[12:15], v[152:155], v[226:229], v[12:15]
	v_mfma_f32_16x16x32_bf16 v[64:67], v[148:151], v[180:183], v[64:67]
	v_mfma_f32_16x16x32_bf16 v[60:63], v[156:159], v[180:183], v[60:63]
	v_mfma_f32_16x16x32_bf16 v[48:51], v[148:151], v[214:217], v[48:51]
	v_mfma_f32_16x16x32_bf16 v[44:47], v[156:159], v[214:217], v[44:47]
	v_mfma_f32_16x16x32_bf16 v[32:35], v[148:151], v[222:225], v[32:35]
	v_mfma_f32_16x16x32_bf16 v[28:31], v[156:159], v[222:225], v[28:31]
	v_mfma_f32_16x16x32_bf16 v[16:19], v[148:151], v[230:233], v[16:19]
	v_mfma_f32_16x16x32_bf16 v[12:15], v[156:159], v[230:233], v[12:15]
	s_setprio 0
	s_setprio 1
	v_mfma_f32_16x16x32_bf16 v[56:59], v[160:163], v[176:179], v[56:59]
	v_mfma_f32_16x16x32_bf16 v[52:55], v[168:171], v[176:179], v[52:55]
	v_mfma_f32_16x16x32_bf16 v[40:43], v[160:163], v[184:187], v[40:43]
	v_mfma_f32_16x16x32_bf16 v[36:39], v[168:171], v[184:187], v[36:39]
	v_mfma_f32_16x16x32_bf16 v[24:27], v[160:163], v[218:221], v[24:27]
	v_mfma_f32_16x16x32_bf16 v[20:23], v[168:171], v[218:221], v[20:23]
	v_mfma_f32_16x16x32_bf16 v[8:11], v[160:163], v[226:229], v[8:11]
	v_mfma_f32_16x16x32_bf16 v[4:7], v[168:171], v[226:229], v[4:7]
	v_mfma_f32_16x16x32_bf16 v[56:59], v[164:167], v[180:183], v[56:59]
	v_mfma_f32_16x16x32_bf16 v[52:55], v[172:175], v[180:183], v[52:55]
	v_mfma_f32_16x16x32_bf16 v[40:43], v[164:167], v[214:217], v[40:43]
	v_mfma_f32_16x16x32_bf16 v[36:39], v[172:175], v[214:217], v[36:39]
	v_mfma_f32_16x16x32_bf16 v[24:27], v[164:167], v[222:225], v[24:27]
	v_mfma_f32_16x16x32_bf16 v[20:23], v[172:175], v[222:225], v[20:23]
	v_mfma_f32_16x16x32_bf16 v[8:11], v[164:167], v[230:233], v[8:11]
	v_mfma_f32_16x16x32_bf16 v[4:7], v[172:175], v[230:233], v[4:7]
	s_setprio 0
	s_barrier
	s_add_i32 s44, 0, 0x18000
	s_add_i32 s45, 0, 0x1c000
	v_add_u32_e32 v156, s44, v210
	v_add_u32_e32 v172, s45, v210
	ds_read_b128 v[144:147], v156
	ds_read_b128 v[148:151], v156 offset:1024
	ds_read_b128 v[152:155], v156 offset:2048
	ds_read_b128 v[156:159], v156 offset:3072
	ds_read_b128 v[160:163], v172
	ds_read_b128 v[164:167], v172 offset:1024
	ds_read_b128 v[168:171], v172 offset:2048
	ds_read_b128 v[172:175], v172 offset:3072
	s_add_u32 s18, s24, 0xb0000
	s_addc_u32 s19, s25, 0
	s_mov_b32 m0, s49
	ds_read_b128 v[176:179], v212 offset:32768
	ds_read_b128 v[180:183], v212 offset:33792
	ds_read_b128 v[184:187], v212 offset:34816
	ds_read_b128 v[214:217], v212 offset:35840
	ds_read_b128 v[218:221], v212 offset:36864
	ds_read_b128 v[222:225], v212 offset:37888
	ds_read_b128 v[226:229], v212 offset:38912
	ds_read_b128 v[230:233], v212 offset:39936
	global_load_lds_dwordx4 v2, s[18:19]
	s_mov_b32 m0, s50
	s_nop 0
	global_load_lds_dwordx4 v0, s[18:19]
	s_waitcnt vmcnt(8)
	s_waitcnt lgkmcnt(0)
	s_barrier
	s_setprio 1
	s_waitcnt lgkmcnt(0)
	v_mfma_f32_16x16x32_bf16 v[128:131], v[144:147], v[176:179], v[128:131]
	v_mfma_f32_16x16x32_bf16 v[124:127], v[152:155], v[176:179], v[124:127]
	v_mfma_f32_16x16x32_bf16 v[112:115], v[144:147], v[184:187], v[112:115]
	v_mfma_f32_16x16x32_bf16 v[108:111], v[152:155], v[184:187], v[108:111]
	v_mfma_f32_16x16x32_bf16 v[96:99], v[144:147], v[218:221], v[96:99]
	v_mfma_f32_16x16x32_bf16 v[92:95], v[152:155], v[218:221], v[92:95]
	v_mfma_f32_16x16x32_bf16 v[80:83], v[144:147], v[226:229], v[80:83]
	v_mfma_f32_16x16x32_bf16 v[76:79], v[152:155], v[226:229], v[76:79]
	v_mfma_f32_16x16x32_bf16 v[128:131], v[148:151], v[180:183], v[128:131]
	v_mfma_f32_16x16x32_bf16 v[124:127], v[156:159], v[180:183], v[124:127]
	v_mfma_f32_16x16x32_bf16 v[112:115], v[148:151], v[214:217], v[112:115]
	v_mfma_f32_16x16x32_bf16 v[108:111], v[156:159], v[214:217], v[108:111]
	v_mfma_f32_16x16x32_bf16 v[96:99], v[148:151], v[222:225], v[96:99]
	v_mfma_f32_16x16x32_bf16 v[92:95], v[156:159], v[222:225], v[92:95]
	v_mfma_f32_16x16x32_bf16 v[80:83], v[148:151], v[230:233], v[80:83]
	v_mfma_f32_16x16x32_bf16 v[76:79], v[156:159], v[230:233], v[76:79]
	s_setprio 0
	s_setprio 1
	v_mfma_f32_16x16x32_bf16 v[120:123], v[160:163], v[176:179], v[120:123]
	v_mfma_f32_16x16x32_bf16 v[116:119], v[168:171], v[176:179], v[116:119]
	v_mfma_f32_16x16x32_bf16 v[104:107], v[160:163], v[184:187], v[104:107]
	v_mfma_f32_16x16x32_bf16 v[100:103], v[168:171], v[184:187], v[100:103]
	v_mfma_f32_16x16x32_bf16 v[88:91], v[160:163], v[218:221], v[88:91]
	v_mfma_f32_16x16x32_bf16 v[84:87], v[168:171], v[218:221], v[84:87]
	v_mfma_f32_16x16x32_bf16 v[72:75], v[160:163], v[226:229], v[72:75]
	v_mfma_f32_16x16x32_bf16 v[68:71], v[168:171], v[226:229], v[68:71]
	v_mfma_f32_16x16x32_bf16 v[120:123], v[164:167], v[180:183], v[120:123]
	v_mfma_f32_16x16x32_bf16 v[116:119], v[172:175], v[180:183], v[116:119]
	v_mfma_f32_16x16x32_bf16 v[104:107], v[164:167], v[214:217], v[104:107]
	v_mfma_f32_16x16x32_bf16 v[100:103], v[172:175], v[214:217], v[100:103]
	v_mfma_f32_16x16x32_bf16 v[88:91], v[164:167], v[222:225], v[88:91]
	v_mfma_f32_16x16x32_bf16 v[84:87], v[172:175], v[222:225], v[84:87]
	v_mfma_f32_16x16x32_bf16 v[72:75], v[164:167], v[230:233], v[72:75]
	v_mfma_f32_16x16x32_bf16 v[68:71], v[172:175], v[230:233], v[68:71]
	s_setprio 0
	s_barrier
	s_add_i32 s18, s44, s46
	s_add_u32 s100, s22, 0x80
	s_addc_u32 s101, s23, 0
	s_mov_b32 m0, s18
	ds_read_b128 v[176:179], v212 offset:49152
	ds_read_b128 v[180:183], v212 offset:50176
	ds_read_b128 v[184:187], v212 offset:51200
	ds_read_b128 v[214:217], v212 offset:52224
	ds_read_b128 v[218:221], v212 offset:53248
	ds_read_b128 v[222:225], v212 offset:54272
	ds_read_b128 v[226:229], v212 offset:55296
	ds_read_b128 v[230:233], v212 offset:56320
	global_load_lds_dwordx4 v2, s[100:101]
	s_add_i32 m0, s18, 0x2000
	s_add_u32 s18, s22, 0xb0080
	s_addc_u32 s19, s23, 0
	s_add_i32 s22, s45, s46
	global_load_lds_dwordx4 v0, s[100:101]
	s_mov_b32 m0, s22
	s_nop 0
	global_load_lds_dwordx4 v2, s[18:19]
	s_add_i32 m0, s22, 0x2000
	s_nop 0
	global_load_lds_dwordx4 v0, s[18:19]
	s_add_u32 s100, s24, 0x80
	s_addc_u32 s101, s25, 0
	s_mov_b32 m0, s52
	s_nop 0
	global_load_lds_dwordx4 v2, s[100:101]
	s_mov_b32 m0, s53
	s_nop 0
	global_load_lds_dwordx4 v0, s[100:101]
	s_waitcnt vmcnt(8)
	s_waitcnt lgkmcnt(0)
	s_barrier
	s_setprio 1
	s_waitcnt lgkmcnt(0)
	v_mfma_f32_16x16x32_bf16 v[64:67], v[144:147], v[176:179], v[64:67]
	v_mfma_f32_16x16x32_bf16 v[60:63], v[152:155], v[176:179], v[60:63]
	v_mfma_f32_16x16x32_bf16 v[48:51], v[144:147], v[184:187], v[48:51]
	v_mfma_f32_16x16x32_bf16 v[44:47], v[152:155], v[184:187], v[44:47]
	v_mfma_f32_16x16x32_bf16 v[32:35], v[144:147], v[218:221], v[32:35]
	v_mfma_f32_16x16x32_bf16 v[28:31], v[152:155], v[218:221], v[28:31]
	v_mfma_f32_16x16x32_bf16 v[16:19], v[144:147], v[226:229], v[16:19]
	v_mfma_f32_16x16x32_bf16 v[12:15], v[152:155], v[226:229], v[12:15]
	v_mfma_f32_16x16x32_bf16 v[64:67], v[148:151], v[180:183], v[64:67]
	v_mfma_f32_16x16x32_bf16 v[60:63], v[156:159], v[180:183], v[60:63]
	v_mfma_f32_16x16x32_bf16 v[48:51], v[148:151], v[214:217], v[48:51]
	v_mfma_f32_16x16x32_bf16 v[44:47], v[156:159], v[214:217], v[44:47]
	v_mfma_f32_16x16x32_bf16 v[32:35], v[148:151], v[222:225], v[32:35]
	v_mfma_f32_16x16x32_bf16 v[28:31], v[156:159], v[222:225], v[28:31]
	v_mfma_f32_16x16x32_bf16 v[16:19], v[148:151], v[230:233], v[16:19]
	v_mfma_f32_16x16x32_bf16 v[12:15], v[156:159], v[230:233], v[12:15]
	s_setprio 0
	s_setprio 1
	v_mfma_f32_16x16x32_bf16 v[56:59], v[160:163], v[176:179], v[56:59]
	v_mfma_f32_16x16x32_bf16 v[52:55], v[168:171], v[176:179], v[52:55]
	v_mfma_f32_16x16x32_bf16 v[40:43], v[160:163], v[184:187], v[40:43]
	v_mfma_f32_16x16x32_bf16 v[36:39], v[168:171], v[184:187], v[36:39]
	v_mfma_f32_16x16x32_bf16 v[24:27], v[160:163], v[218:221], v[24:27]
	v_mfma_f32_16x16x32_bf16 v[20:23], v[168:171], v[218:221], v[20:23]
	v_mfma_f32_16x16x32_bf16 v[8:11], v[160:163], v[226:229], v[8:11]
	v_mfma_f32_16x16x32_bf16 v[4:7], v[168:171], v[226:229], v[4:7]
	v_mfma_f32_16x16x32_bf16 v[56:59], v[164:167], v[180:183], v[56:59]
	v_mfma_f32_16x16x32_bf16 v[52:55], v[172:175], v[180:183], v[52:55]
	v_mfma_f32_16x16x32_bf16 v[40:43], v[164:167], v[214:217], v[40:43]
	v_mfma_f32_16x16x32_bf16 v[36:39], v[172:175], v[214:217], v[36:39]
	v_mfma_f32_16x16x32_bf16 v[24:27], v[164:167], v[222:225], v[24:27]
	v_mfma_f32_16x16x32_bf16 v[20:23], v[172:175], v[222:225], v[20:23]
	v_mfma_f32_16x16x32_bf16 v[8:11], v[164:167], v[230:233], v[8:11]
	v_mfma_f32_16x16x32_bf16 v[4:7], v[172:175], v[230:233], v[4:7]
	s_setprio 0
	s_barrier
	s_add_i32 s15, s15, 2
	s_add_u32 s13, s13, 0x100
	s_addc_u32 s14, s14, 0
	s_cmp_gt_u32 s15, 41
	s_mov_b64 s[44:45], s[42:43]
	s_cbranch_scc0 .LBB0_811
	s_and_b64 vcc, exec, s[4:5]
	s_cbranch_vccz .LBB0_814
	s_barrier

.LBB0_928:
	s_add_u32 s18, s40, 0xfffc0080
	s_addc_u32 s19, s41, -1
	s_add_i32 s52, 0, 0x10000
	s_cmp_eq_u32 s51, 12
	s_cselect_b32 s25, s7, s19
	s_cselect_b32 s24, s13, s18
	s_cselect_b32 s23, s5, s43
	s_cselect_b32 s22, s17, s42
	s_add_i32 s53, 0, 0x14000
	v_add_u32_e32 v166, s52, v152
	v_add_u32_e32 v182, s53, v152
	ds_read_b128 v[148:151], v166
	ds_read_b128 v[158:161], v166 offset:1024
	ds_read_b128 v[162:165], v166 offset:2048
	ds_read_b128 v[166:169], v166 offset:3072
	ds_read_b128 v[170:173], v182
	ds_read_b128 v[174:177], v182 offset:1024
	ds_read_b128 v[178:181], v182 offset:2048
	ds_read_b128 v[182:185], v182 offset:3072
	s_add_i32 m0, s29, 0xc000
	ds_read_b128 v[186:189], v157
	ds_read_b128 v[208:211], v157 offset:1024
	ds_read_b128 v[212:215], v157 offset:2048
	ds_read_b128 v[216:219], v157 offset:3072
	ds_read_b128 v[220:223], v157 offset:4096
	ds_read_b128 v[224:227], v157 offset:5120
	ds_read_b128 v[228:231], v157 offset:6144
	ds_read_b128 v[232:235], v157 offset:7168
	global_load_lds_dwordx4 v144, s[40:41]
	s_add_i32 m0, s29, 0xe000
	s_nop 0
	global_load_lds_dwordx4 v146, s[40:41]
	s_waitcnt vmcnt(8)
	s_waitcnt lgkmcnt(0)
	s_barrier
	s_setprio 1
	s_waitcnt lgkmcnt(0)
	v_mfma_f32_16x16x32_bf16 v[128:131], v[148:151], v[186:189], v[128:131]
	v_mfma_f32_16x16x32_bf16 v[124:127], v[162:165], v[186:189], v[124:127]
	v_mfma_f32_16x16x32_bf16 v[116:119], v[148:151], v[212:215], v[116:119]
	v_mfma_f32_16x16x32_bf16 v[108:111], v[162:165], v[212:215], v[108:111]
	v_mfma_f32_16x16x32_bf16 v[100:103], v[148:151], v[220:223], v[100:103]
	v_mfma_f32_16x16x32_bf16 v[92:95], v[162:165], v[220:223], v[92:95]
	v_mfma_f32_16x16x32_bf16 v[84:87], v[148:151], v[228:231], v[84:87]
	v_mfma_f32_16x16x32_bf16 v[76:79], v[162:165], v[228:231], v[76:79]
	v_mfma_f32_16x16x32_bf16 v[128:131], v[158:161], v[208:211], v[128:131]
	v_mfma_f32_16x16x32_bf16 v[124:127], v[166:169], v[208:211], v[124:127]
	v_mfma_f32_16x16x32_bf16 v[116:119], v[158:161], v[216:219], v[116:119]
	v_mfma_f32_16x16x32_bf16 v[108:111], v[166:169], v[216:219], v[108:111]
	v_mfma_f32_16x16x32_bf16 v[100:103], v[158:161], v[224:227], v[100:103]
	v_mfma_f32_16x16x32_bf16 v[92:95], v[166:169], v[224:227], v[92:95]
	v_mfma_f32_16x16x32_bf16 v[84:87], v[158:161], v[232:235], v[84:87]
	v_mfma_f32_16x16x32_bf16 v[76:79], v[166:169], v[232:235], v[76:79]
	s_setprio 0
	s_setprio 1
	v_mfma_f32_16x16x32_bf16 v[120:123], v[170:173], v[186:189], v[120:123]
	v_mfma_f32_16x16x32_bf16 v[112:115], v[178:181], v[186:189], v[112:115]
	v_mfma_f32_16x16x32_bf16 v[104:107], v[170:173], v[212:215], v[104:107]
	v_mfma_f32_16x16x32_bf16 v[96:99], v[178:181], v[212:215], v[96:99]
	v_mfma_f32_16x16x32_bf16 v[88:91], v[170:173], v[220:223], v[88:91]
	v_mfma_f32_16x16x32_bf16 v[80:83], v[178:181], v[220:223], v[80:83]
	v_mfma_f32_16x16x32_bf16 v[72:75], v[170:173], v[228:231], v[72:75]
	v_mfma_f32_16x16x32_bf16 v[68:71], v[178:181], v[228:231], v[68:71]
	v_mfma_f32_16x16x32_bf16 v[120:123], v[174:177], v[208:211], v[120:123]
	v_mfma_f32_16x16x32_bf16 v[112:115], v[182:185], v[208:211], v[112:115]
	v_mfma_f32_16x16x32_bf16 v[104:107], v[174:177], v[216:219], v[104:107]
	v_mfma_f32_16x16x32_bf16 v[96:99], v[182:185], v[216:219], v[96:99]
	v_mfma_f32_16x16x32_bf16 v[88:91], v[174:177], v[224:227], v[88:91]
	v_mfma_f32_16x16x32_bf16 v[80:83], v[182:185], v[224:227], v[80:83]
	v_mfma_f32_16x16x32_bf16 v[72:75], v[174:177], v[232:235], v[72:75]
	v_mfma_f32_16x16x32_bf16 v[68:71], v[182:185], v[232:235], v[68:71]
	s_setprio 0
	s_barrier
	s_add_i32 s18, s52, s28
	s_mov_b32 m0, s18
	ds_read_b128 v[186:189], v157 offset:16384
	ds_read_b128 v[208:211], v157 offset:17408
	ds_read_b128 v[212:215], v157 offset:18432
	ds_read_b128 v[216:219], v157 offset:19456
	ds_read_b128 v[220:223], v157 offset:20480
	ds_read_b128 v[224:227], v157 offset:21504
	ds_read_b128 v[228:231], v157 offset:22528
	ds_read_b128 v[232:235], v157 offset:23552
	global_load_lds_dwordx4 v2, s[22:23]
	s_add_i32 m0, s18, 0x2000
	s_add_u32 s18, s22, 0x10000
	s_addc_u32 s19, s23, 0
	s_add_i32 s52, s53, s28
	global_load_lds_dwordx4 v142, s[22:23]
	s_mov_b32 m0, s52
	s_nop 0
	global_load_lds_dwordx4 v2, s[18:19]
	s_add_i32 m0, s52, 0x2000
	s_nop 0
	global_load_lds_dwordx4 v142, s[18:19]
	s_mov_b32 m0, s29
	s_nop 0
	global_load_lds_dwordx4 v0, s[24:25]
	s_mov_b32 m0, s44
	s_nop 0
	global_load_lds_dwordx4 v140, s[24:25]
	s_waitcnt vmcnt(8)
	s_waitcnt lgkmcnt(0)
	s_barrier
	s_setprio 1
	s_waitcnt lgkmcnt(0)
	v_mfma_f32_16x16x32_bf16 v[64:67], v[148:151], v[186:189], v[64:67]
	v_mfma_f32_16x16x32_bf16 v[60:63], v[162:165], v[186:189], v[60:63]
	v_mfma_f32_16x16x32_bf16 v[52:55], v[148:151], v[212:215], v[52:55]
	v_mfma_f32_16x16x32_bf16 v[44:47], v[162:165], v[212:215], v[44:47]
	v_mfma_f32_16x16x32_bf16 v[36:39], v[148:151], v[220:223], v[36:39]
	v_mfma_f32_16x16x32_bf16 v[28:31], v[162:165], v[220:223], v[28:31]
	v_mfma_f32_16x16x32_bf16 v[20:23], v[148:151], v[228:231], v[20:23]
	v_mfma_f32_16x16x32_bf16 v[12:15], v[162:165], v[228:231], v[12:15]
	v_mfma_f32_16x16x32_bf16 v[64:67], v[158:161], v[208:211], v[64:67]
	v_mfma_f32_16x16x32_bf16 v[60:63], v[166:169], v[208:211], v[60:63]
	v_mfma_f32_16x16x32_bf16 v[52:55], v[158:161], v[216:219], v[52:55]
	v_mfma_f32_16x16x32_bf16 v[44:47], v[166:169], v[216:219], v[44:47]
	v_mfma_f32_16x16x32_bf16 v[36:39], v[158:161], v[224:227], v[36:39]
	v_mfma_f32_16x16x32_bf16 v[28:31], v[166:169], v[224:227], v[28:31]
	v_mfma_f32_16x16x32_bf16 v[20:23], v[158:161], v[232:235], v[20:23]
	v_mfma_f32_16x16x32_bf16 v[12:15], v[166:169], v[232:235], v[12:15]
	s_setprio 0
	s_setprio 1
	v_mfma_f32_16x16x32_bf16 v[56:59], v[170:173], v[186:189], v[56:59]
	v_mfma_f32_16x16x32_bf16 v[48:51], v[178:181], v[186:189], v[48:51]
	v_mfma_f32_16x16x32_bf16 v[40:43], v[170:173], v[212:215], v[40:43]
	v_mfma_f32_16x16x32_bf16 v[32:35], v[178:181], v[212:215], v[32:35]
	v_mfma_f32_16x16x32_bf16 v[24:27], v[170:173], v[220:223], v[24:27]
	v_mfma_f32_16x16x32_bf16 v[16:19], v[178:181], v[220:223], v[16:19]
	v_mfma_f32_16x16x32_bf16 v[8:11], v[170:173], v[228:231], v[8:11]
	v_mfma_f32_16x16x32_bf16 v[4:7], v[178:181], v[228:231], v[4:7]
	v_mfma_f32_16x16x32_bf16 v[56:59], v[174:177], v[208:211], v[56:59]
	v_mfma_f32_16x16x32_bf16 v[48:51], v[182:185], v[208:211], v[48:51]
	v_mfma_f32_16x16x32_bf16 v[40:43], v[174:177], v[216:219], v[40:43]
	v_mfma_f32_16x16x32_bf16 v[32:35], v[182:185], v[216:219], v[32:35]
	v_mfma_f32_16x16x32_bf16 v[24:27], v[174:177], v[224:227], v[24:27]
	v_mfma_f32_16x16x32_bf16 v[16:19], v[182:185], v[224:227], v[16:19]
	v_mfma_f32_16x16x32_bf16 v[8:11], v[174:177], v[232:235], v[8:11]
	v_mfma_f32_16x16x32_bf16 v[4:7], v[182:185], v[232:235], v[4:7]
	s_setprio 0
	s_barrier
	s_add_i32 s52, 0, 0x18000
	s_add_i32 s53, 0, 0x1c000
	v_add_u32_e32 v166, s52, v152
	v_add_u32_e32 v182, s53, v152
	ds_read_b128 v[148:151], v166
	ds_read_b128 v[158:161], v166 offset:1024
	ds_read_b128 v[162:165], v166 offset:2048
	ds_read_b128 v[166:169], v166 offset:3072
	ds_read_b128 v[170:173], v182
	ds_read_b128 v[174:177], v182 offset:1024
	ds_read_b128 v[178:181], v182 offset:2048
	ds_read_b128 v[182:185], v182 offset:3072
	s_add_u32 s18, s24, 0x40000
	s_addc_u32 s19, s25, 0
	s_mov_b32 m0, s45
	ds_read_b128 v[186:189], v157 offset:32768
	ds_read_b128 v[208:211], v157 offset:33792
	ds_read_b128 v[212:215], v157 offset:34816
	ds_read_b128 v[216:219], v157 offset:35840
	ds_read_b128 v[220:223], v157 offset:36864
	ds_read_b128 v[224:227], v157 offset:37888
	ds_read_b128 v[228:231], v157 offset:38912
	ds_read_b128 v[232:235], v157 offset:39936
	global_load_lds_dwordx4 v0, s[18:19]
	s_mov_b32 m0, s46
	s_nop 0
	global_load_lds_dwordx4 v140, s[18:19]
	s_waitcnt vmcnt(8)
	s_waitcnt lgkmcnt(0)
	s_barrier
	s_setprio 1
	s_waitcnt lgkmcnt(0)
	v_mfma_f32_16x16x32_bf16 v[128:131], v[148:151], v[186:189], v[128:131]
	v_mfma_f32_16x16x32_bf16 v[124:127], v[162:165], v[186:189], v[124:127]
	v_mfma_f32_16x16x32_bf16 v[116:119], v[148:151], v[212:215], v[116:119]
	v_mfma_f32_16x16x32_bf16 v[108:111], v[162:165], v[212:215], v[108:111]
	v_mfma_f32_16x16x32_bf16 v[100:103], v[148:151], v[220:223], v[100:103]
	v_mfma_f32_16x16x32_bf16 v[92:95], v[162:165], v[220:223], v[92:95]
	v_mfma_f32_16x16x32_bf16 v[84:87], v[148:151], v[228:231], v[84:87]
	v_mfma_f32_16x16x32_bf16 v[76:79], v[162:165], v[228:231], v[76:79]
	v_mfma_f32_16x16x32_bf16 v[128:131], v[158:161], v[208:211], v[128:131]
	v_mfma_f32_16x16x32_bf16 v[124:127], v[166:169], v[208:211], v[124:127]
	v_mfma_f32_16x16x32_bf16 v[116:119], v[158:161], v[216:219], v[116:119]
	v_mfma_f32_16x16x32_bf16 v[108:111], v[166:169], v[216:219], v[108:111]
	v_mfma_f32_16x16x32_bf16 v[100:103], v[158:161], v[224:227], v[100:103]
	v_mfma_f32_16x16x32_bf16 v[92:95], v[166:169], v[224:227], v[92:95]
	v_mfma_f32_16x16x32_bf16 v[84:87], v[158:161], v[232:235], v[84:87]
	v_mfma_f32_16x16x32_bf16 v[76:79], v[166:169], v[232:235], v[76:79]
	s_setprio 0
	s_setprio 1
	v_mfma_f32_16x16x32_bf16 v[120:123], v[170:173], v[186:189], v[120:123]
	v_mfma_f32_16x16x32_bf16 v[112:115], v[178:181], v[186:189], v[112:115]
	v_mfma_f32_16x16x32_bf16 v[104:107], v[170:173], v[212:215], v[104:107]
	v_mfma_f32_16x16x32_bf16 v[96:99], v[178:181], v[212:215], v[96:99]
	v_mfma_f32_16x16x32_bf16 v[88:91], v[170:173], v[220:223], v[88:91]
	v_mfma_f32_16x16x32_bf16 v[80:83], v[178:181], v[220:223], v[80:83]
	v_mfma_f32_16x16x32_bf16 v[72:75], v[170:173], v[228:231], v[72:75]
	v_mfma_f32_16x16x32_bf16 v[68:71], v[178:181], v[228:231], v[68:71]
	v_mfma_f32_16x16x32_bf16 v[120:123], v[174:177], v[208:211], v[120:123]
	v_mfma_f32_16x16x32_bf16 v[112:115], v[182:185], v[208:211], v[112:115]
	v_mfma_f32_16x16x32_bf16 v[104:107], v[174:177], v[216:219], v[104:107]
	v_mfma_f32_16x16x32_bf16 v[96:99], v[182:185], v[216:219], v[96:99]
	v_mfma_f32_16x16x32_bf16 v[88:91], v[174:177], v[224:227], v[88:91]
	v_mfma_f32_16x16x32_bf16 v[80:83], v[182:185], v[224:227], v[80:83]
	v_mfma_f32_16x16x32_bf16 v[72:75], v[174:177], v[232:235], v[72:75]
	v_mfma_f32_16x16x32_bf16 v[68:71], v[182:185], v[232:235], v[68:71]
	s_setprio 0
	s_barrier
	s_add_i32 s18, s52, s28
	s_add_u32 s100, s22, 0x80
	s_addc_u32 s101, s23, 0
	s_mov_b32 m0, s18
	ds_read_b128 v[186:189], v157 offset:49152
	ds_read_b128 v[208:211], v157 offset:50176
	ds_read_b128 v[212:215], v157 offset:51200
	ds_read_b128 v[216:219], v157 offset:52224
	ds_read_b128 v[220:223], v157 offset:53248
	ds_read_b128 v[224:227], v157 offset:54272
	ds_read_b128 v[228:231], v157 offset:55296
	ds_read_b128 v[232:235], v157 offset:56320
	global_load_lds_dwordx4 v2, s[100:101]
	s_add_i32 m0, s18, 0x2000
	s_add_u32 s18, s22, 0x10080
	s_addc_u32 s19, s23, 0
	s_add_i32 s22, s53, s28
	global_load_lds_dwordx4 v142, s[100:101]
	s_mov_b32 m0, s22
	s_nop 0
	global_load_lds_dwordx4 v2, s[18:19]
	s_add_i32 m0, s22, 0x2000
	s_nop 0
	global_load_lds_dwordx4 v142, s[18:19]
	s_add_u32 s100, s24, 0x80
	s_addc_u32 s101, s25, 0
	s_mov_b32 m0, s47
	s_nop 0
	global_load_lds_dwordx4 v0, s[100:101]
	s_mov_b32 m0, s48
	s_nop 0
	global_load_lds_dwordx4 v140, s[100:101]
	s_waitcnt vmcnt(8)
	s_waitcnt lgkmcnt(0)
	s_barrier
	s_setprio 1
	s_waitcnt lgkmcnt(0)
	v_mfma_f32_16x16x32_bf16 v[64:67], v[148:151], v[186:189], v[64:67]
	v_mfma_f32_16x16x32_bf16 v[60:63], v[162:165], v[186:189], v[60:63]
	v_mfma_f32_16x16x32_bf16 v[52:55], v[148:151], v[212:215], v[52:55]
	v_mfma_f32_16x16x32_bf16 v[44:47], v[162:165], v[212:215], v[44:47]
	v_mfma_f32_16x16x32_bf16 v[36:39], v[148:151], v[220:223], v[36:39]
	v_mfma_f32_16x16x32_bf16 v[28:31], v[162:165], v[220:223], v[28:31]
	v_mfma_f32_16x16x32_bf16 v[20:23], v[148:151], v[228:231], v[20:23]
	v_mfma_f32_16x16x32_bf16 v[12:15], v[162:165], v[228:231], v[12:15]
	v_mfma_f32_16x16x32_bf16 v[64:67], v[158:161], v[208:211], v[64:67]
	v_mfma_f32_16x16x32_bf16 v[60:63], v[166:169], v[208:211], v[60:63]
	v_mfma_f32_16x16x32_bf16 v[52:55], v[158:161], v[216:219], v[52:55]
	v_mfma_f32_16x16x32_bf16 v[44:47], v[166:169], v[216:219], v[44:47]
	v_mfma_f32_16x16x32_bf16 v[36:39], v[158:161], v[224:227], v[36:39]
	v_mfma_f32_16x16x32_bf16 v[28:31], v[166:169], v[224:227], v[28:31]
	v_mfma_f32_16x16x32_bf16 v[20:23], v[158:161], v[232:235], v[20:23]
	v_mfma_f32_16x16x32_bf16 v[12:15], v[166:169], v[232:235], v[12:15]
	s_setprio 0
	s_setprio 1
	v_mfma_f32_16x16x32_bf16 v[56:59], v[170:173], v[186:189], v[56:59]
	v_mfma_f32_16x16x32_bf16 v[48:51], v[178:181], v[186:189], v[48:51]
	v_mfma_f32_16x16x32_bf16 v[40:43], v[170:173], v[212:215], v[40:43]
	v_mfma_f32_16x16x32_bf16 v[32:35], v[178:181], v[212:215], v[32:35]
	v_mfma_f32_16x16x32_bf16 v[24:27], v[170:173], v[220:223], v[24:27]
	v_mfma_f32_16x16x32_bf16 v[16:19], v[178:181], v[220:223], v[16:19]
	v_mfma_f32_16x16x32_bf16 v[8:11], v[170:173], v[228:231], v[8:11]
	v_mfma_f32_16x16x32_bf16 v[4:7], v[178:181], v[228:231], v[4:7]
	v_mfma_f32_16x16x32_bf16 v[56:59], v[174:177], v[208:211], v[56:59]
	v_mfma_f32_16x16x32_bf16 v[48:51], v[182:185], v[208:211], v[48:51]
	v_mfma_f32_16x16x32_bf16 v[40:43], v[174:177], v[216:219], v[40:43]
	v_mfma_f32_16x16x32_bf16 v[32:35], v[182:185], v[216:219], v[32:35]
	v_mfma_f32_16x16x32_bf16 v[24:27], v[174:177], v[224:227], v[24:27]
	v_mfma_f32_16x16x32_bf16 v[16:19], v[182:185], v[224:227], v[16:19]
	v_mfma_f32_16x16x32_bf16 v[8:11], v[174:177], v[232:235], v[8:11]
	v_mfma_f32_16x16x32_bf16 v[4:7], v[182:185], v[232:235], v[4:7]
	s_setprio 0
	s_barrier
	s_add_i32 s51, s51, 2
	s_add_u32 s40, s40, 0x100
	s_addc_u32 s41, s41, 0
	s_add_u32 s42, s42, 0x100
	s_addc_u32 s43, s43, 0
	s_cmp_gt_u32 s51, 13
	s_cbranch_scc0 .LBB0_928
	s_lshl_b32 s5, s16, 8
	s_and_b64 vcc, exec, s[2:3]
	s_cbranch_vccz .LBB0_931
	v_or_b32_e32 v148, s5, v154
	v_ashrrev_i32_e32 v149, 31, v148
	v_lshlrev_b64 v[148:149], 6, v[148:149]
	v_lshl_add_u64 v[166:167], s[74:75], 0, v[148:149]
	global_load_dwordx4 v[148:151], v[166:167], off
	global_load_dwordx4 v[158:161], v[166:167], off offset:32
	global_load_dwordx4 v[162:165], v[166:167], off offset:16
	s_nop 0
	global_load_dwordx4 v[166:169], v[166:167], off offset:48
	s_barrier
